# v16
# speedup vs baseline: 1.0284x; 1.0262x over previous
; __global__ void __launch_bounds__(512, 2) hymba_fwd(Params p) {
;     ...
;   phase_prep(p, lds);
;   grid.sync();
;   phase_inproj(p, lds);
.LBB0_37:
	s_or_b64 exec, exec, s[0:1]
	v_lshrrev_b32_e32 v1, 20, v0
	v_lshrrev_b32_e32 v0, 10, v0
	v_or_b32_e32 v0, v0, v1
	s_movk_i32 s0, 0x3ff
	v_and_or_b32 v0, v0, s0, v164
	s_waitcnt lgkmcnt(0)
	v_cmp_eq_u32_e64 s[58:59], 0, v0
	s_barrier
	s_and_saveexec_b64 s[0:1], s[58:59]
	s_cbranch_execz .LBB0_47
	buffer_wbl2 sc1
	s_waitcnt vmcnt(0)
	s_load_dwordx2 s[4:5], s[92:93], 0x58
	v_mov_b32_e32 v2, 0
	s_and_b32 s6, s2, 7
	s_mov_b32 s7, 1
	v_writelane_b32 v255, s7, 61
	s_lshl_b32 s6, s6, 6
	s_add_i32 s6, s6, 0x1f80800
	v_mov_b32_e32 v1, s6
	s_waitcnt lgkmcnt(0)
	global_load_dword v0, v2, s[4:5] offset:40
	global_load_dword v3, v2, s[4:5] offset:32 sc1
	s_waitcnt vmcnt(0)
	v_readfirstlane_b32 s6, v3
	s_nop 3
	s_and_b32 vcc_hi, s6, 0xffff0000
	v_mov_b32_e32 v3, 1
	global_atomic_add v3, v1, v3, s[90:91] sc0
	s_waitcnt vmcnt(0)
	v_readfirstlane_b32 s6, v0
	s_nop 3
	s_lshr_b32 vcc_lo, s6, 3
	s_mul_i32 s7, s7, vcc_lo
	v_readfirstlane_b32 s6, v3
	s_nop 3
	s_add_i32 s6, s6, 1
	s_cmp_eq_u32 s6, s7
	s_cbranch_scc0 .Lgb0_poll
	v_mov_b32_e32 v3, vcc_lo
	global_atomic_add v3, v2, v3, s[4:5] offset:32 sc0
	s_waitcnt vmcnt(0)
	v_readfirstlane_b32 s6, v3
	v_readfirstlane_b32 s7, v0
	s_nop 3
	s_and_b32 s6, s6, 0xffff
	s_add_i32 s6, s6, vcc_lo
	s_cmp_eq_u32 s6, s7
	s_cbranch_scc0 .Lgb0_poll
	s_sub_i32 s6, 0x10000, s7
	v_mov_b32_e32 v3, s6
	global_atomic_add v2, v3, s[4:5] offset:32
.Lgb0_poll:
	global_load_dword v3, v2, s[4:5] offset:32 sc1
	s_waitcnt vmcnt(0)
	v_readfirstlane_b32 s6, v3
	s_nop 3
	s_and_b32 s6, s6, 0xffff0000
	s_cmp_lg_u32 s6, vcc_hi
	s_cbranch_scc1 .Lgb0_done
	s_sleep 1
	s_branch .Lgb0_poll
.Lgb0_done:
	v_writelane_b32 v255, s6, 62
	buffer_inv sc1
.LBB0_47:
	s_or_b64 exec, exec, s[0:1]
	s_and_b32 s3, s2, 7
	s_lshr_b32 s1, s2, 3
	s_mul_i32 s0, s3, 0x1e47
	s_lshr_b32 s0, s0, 3
	s_add_i32 s33, s0, s1
	s_mul_i32 s0, s3, 0x1e47
	v_writelane_b32 v255, s1, 1
	s_addk_i32 s0, 0x1e47
	v_writelane_b32 v255, s3, 2
	s_lshr_b32 s38, s0, 3
	s_mov_b64 s[0:1], s[40:41]
	s_mov_b64 s[2:3], s[42:43]
	s_mov_b64 s[10:11], s[50:51]
	s_mov_b64 s[12:13], s[52:53]
	v_writelane_b32 v255, s0, 3
	s_lshr_b32 s60, s88, 3
	v_mov_b32_e32 v140, v164
	v_writelane_b32 v255, s1, 4
	v_writelane_b32 v255, s2, 5
	v_writelane_b32 v255, s3, 6
	v_writelane_b32 v255, s4, 7
	v_writelane_b32 v255, s5, 8
	v_writelane_b32 v255, s6, 9
	v_writelane_b32 v255, s7, 10
	v_writelane_b32 v255, s8, 11
	v_writelane_b32 v255, s9, 12
	v_writelane_b32 v255, s10, 13
	v_writelane_b32 v255, s11, 14
	v_writelane_b32 v255, s12, 15
	v_writelane_b32 v255, s13, 16
	v_writelane_b32 v255, s14, 17
	s_cmp_ge_u32 s33, s38
	v_writelane_b32 v255, s15, 18
	s_barrier
	s_cbranch_scc1 .LBB0_125
	s_add_u32 s39, s90, 0xcfa4000
	s_addc_u32 s40, s91, 0
	s_add_u32 s0, s90, 0x2764000
	s_addc_u32 s1, s91, 0
	s_movk_i32 s41, 0x2000
	v_mov_b32_e32 v133, 0
	s_mov_b32 s42, 0x10000
	s_mov_b32 s43, 0x14000
	s_mov_b64 s[12:13], 0x80
	s_mov_b32 s44, 0x18000
	s_mov_b64 s[14:15], 0x40080
	s_mov_b32 s45, 0x1c000
	s_mov_b64 s[16:17], 0x100
	s_mov_b64 s[18:19], 0x40100
	s_mov_b64 s[20:21], 0x180
	s_mov_b64 s[22:23], 0x40180
	s_movk_i32 s46, 0x100
	s_mov_b32 s25, 0
	s_mov_b32 s47, 0x15080
	s_mov_b32 s26, 0x3e38aa3b
	s_movk_i32 s48, 0x210
	s_movk_i32 s49, 0x60
	s_movk_i32 s50, 0x600
	s_movk_i32 s51, 0x2440
	s_movk_i32 s52, 0xff84
	s_movk_i32 s53, 0xc00
	s_movk_i32 s54, 0x5ff
	s_movk_i32 s55, 0x17ff
	v_mov_b32_e32 v141, 1
	v_mbcnt_hi_u32_b32 v142, -1, v144
	v_mov_b32_e32 v143, 0x10800
	v_mov_b32_e32 v145, 0x12900
	s_branch .LBB0_51

; #define STAGE(P, BASE, LD, br, kt) STAGE_(P, BASE, LD, br, kt, (&(BASE) == &A))
; #define BAR __builtin_amdgcn_s_barrier()
; DEVI void gemm_core(const u16* __restrict__ A, size_t lda, const u16* __restrict__ Bt, size_t ldb, int nt,
;                     char* ldsc, f32x4 (&acc)[2][2][4][2]) {
;     ...
;   {
;     int r0, c0, r1, c1;
;     g_stage_rc(tid * 16, r0, c0);
;     g_stage_rc(tid * 16 + 8192, r1, c1);
;     offA0 = (unsigned)(r0 * (int)lda + c0); offA1 = (unsigned)(r1 * (int)lda + c1);
;     offB0 = (unsigned)(r0 * (int)ldb + c0); offB1 = (unsigned)(r1 * (int)ldb + c1);
;   }
;   STAGE(SB(0, 0), Bt, ldb, 0, 0); STAGE(SA(0, 0), A, lda, 0, 0);
;   STAGE(SB(0, 1), Bt, ldb, HALF, 0); STAGE(SA(0, 1), A, lda, HALF, 0);
;   if (wr == 1) BAR;
; DEVI void tile_decode(int j, int MT, int NT, int W, int& mt, int& nt) {
;   const int nbf = NT / W;
;   const int band = j / (W * MT);
;   if (band < nbf) { int r = j - band * W * MT; mt = r / W; nt = band * W + r % W; }
;   else { const int Wl = NT - nbf * W; int r = j - nbf * W * MT; mt = r / Wl; nt = nbf * W + r % Wl; }
; }
.LBB0_51:
	s_cmpk_lt_u32 s33, 0x17b2
	s_cbranch_scc0 .Ltd_last
	s_mul_hi_u32 s2, s33, 0x81a55963
	s_lshr_b32 s2, s2, 10
	s_mul_i32 s3, s2, 6
	s_mulk_i32 s2, 0xf81a
	s_add_i32 s2, s2, s33
	s_mul_hi_i32 s4, s2, 0x2aaaaaab
	s_lshr_b32 s5, s4, 31
	s_add_i32 s28, s4, s5
	s_mul_i32 s4, s28, 6
	s_sub_i32 s2, s2, s4
	s_add_i32 s30, s2, s3
	s_branch .Ltd_done
.Ltd_last:
	s_add_i32 s2, s33, 0xffffe84e
	s_mul_hi_u32 s28, s2, 0x33333334
	s_mul_i32 s4, s28, 5
	s_sub_i32 s2, s2, s4
	s_add_i32 s30, s2, 18
.Ltd_done:
	v_mov_b32_e32 v146, v164
	s_ashr_i32 s29, s28, 31
	v_ashrrev_i32_e32 v0, 31, v146
	v_lshrrev_b32_e32 v0, 26, v0
	v_add_u32_e32 v0, v146, v0
	v_ashrrev_i32_e32 v8, 6, v0
	v_bfe_i32 v0, v146, 27, 1
	v_lshlrev_b32_e32 v147, 4, v146
	v_lshrrev_b32_e32 v0, 22, v0
	v_add_u32_e32 v0, v147, v0
	v_and_b32_e32 v0, 0xfffffc00, v0
	v_sub_u32_e32 v0, v147, v0
	v_lshrrev_b32_e32 v1, 4, v0
	v_bitop3_b32 v0, v1, v0, 32 bitop3:0x6c
	v_ashrrev_i32_e32 v2, 31, v0
	v_lshrrev_b32_e32 v2, 26, v2
	v_add_u32_e32 v2, v0, v2
	v_ashrrev_i32_e32 v9, 6, v2
	v_and_b32_e32 v2, 0xc0, v2
	v_sub_u32_e32 v0, v0, v2
	v_add_u32_e32 v152, 0x2000, v147
	v_ashrrev_i16_sdwa v12, v141, sext(v0) dst_sel:DWORD dst_unused:UNUSED_PAD src0_sel:DWORD src1_sel:BYTE_0
	v_ashrrev_i32_e32 v0, 31, v152
	v_lshrrev_b32_e32 v0, 22, v0
	v_add_u32_e32 v0, v152, v0
	v_ashrrev_i32_e32 v11, 10, v0
	v_mul_i32_i24_e32 v0, 0x400, v11
	v_sub_u32_e32 v0, v152, v0
	v_lshrrev_b32_e32 v2, 4, v0
	s_lshl_b64 s[2:3], s[28:29], 19
	v_lshlrev_b32_e32 v3, 5, v8
	v_bitop3_b32 v0, v2, v0, 32 bitop3:0x6c
	s_add_u32 s6, s86, s2
	v_and_b32_e32 v10, 32, v3
	v_ashrrev_i32_e32 v3, 31, v0
	s_addc_u32 s7, s87, s3
	s_ashr_i32 s31, s30, 31
	v_lshrrev_b32_e32 v3, 26, v3
	s_lshl_b64 s[2:3], s[30:31], 19
	v_lshlrev_b32_e32 v1, 3, v8
	v_add_u32_e32 v3, v0, v3
	s_add_u32 s8, s90, s2
	v_and_b32_e32 v1, 0x3ffff0, v1
	v_lshlrev_b32_e32 v2, 3, v11
	v_ashrrev_i32_e32 v13, 6, v3
	v_and_b32_e32 v3, 0xc0, v3
	s_addc_u32 s9, s91, s3
	s_and_b32 s10, s30, -4
	v_add_u32_e32 v1, v9, v1
	v_and_b32_e32 v2, 0x3ffff0, v2
	v_lshlrev_b32_e32 v4, 5, v11
	v_sub_u32_e32 v0, v0, v3
	s_cmp_lg_u32 s10, 8
	v_add_u32_e32 v2, v13, v2
	v_and_b32_e32 v14, 32, v4
	v_ashrrev_i16_sdwa v15, v141, sext(v0) dst_sel:DWORD dst_unused:UNUSED_PAD src0_sel:DWORD src1_sel:BYTE_0
	v_lshl_or_b32 v0, v1, 10, v10
	s_cselect_b64 s[2:3], -1, 0
	s_cmp_eq_u32 s10, 8
	v_add_u32_sdwa v132, v0, sext(v12) dst_sel:DWORD dst_unused:UNUSED_PAD src0_sel:DWORD src1_sel:WORD_0
	v_lshl_or_b32 v0, v2, 10, v14
	v_add_u32_e32 v154, 0x10000, v147
	s_cselect_b32 s5, s7, s9
	s_cselect_b32 s4, s6, s8
	s_cselect_b32 s7, s9, s7
	s_cselect_b32 s6, s8, s6
	v_add_u32_sdwa v128, v0, sext(v15) dst_sel:DWORD dst_unused:UNUSED_PAD src0_sel:DWORD src1_sel:WORD_0
	v_lshlrev_b64 v[16:17], 1, v[132:133]
	v_readfirstlane_b32 s8, v154
	v_mov_b32_e32 v129, v133
	v_add_u32_e32 v155, 0x12000, v147
	v_lshl_add_u64 v[0:1], s[6:7], 0, v[16:17]
	s_mov_b32 m0, s8
	v_lshlrev_b64 v[18:19], 1, v[128:129]
	v_readfirstlane_b32 s8, v155
	global_load_lds_dwordx4 v[0:1], off
	v_lshl_add_u64 v[4:5], s[6:7], 0, v[18:19]
	s_mov_b32 m0, s8
	v_readfirstlane_b32 s8, v147
	global_load_lds_dwordx4 v[4:5], off
	v_lshl_add_u64 v[6:7], s[4:5], 0, v[16:17]
	s_mov_b32 m0, s8
	v_readfirstlane_b32 s8, v152
	global_load_lds_dwordx4 v[6:7], off
	s_mov_b32 m0, s8
	s_add_u32 s8, s6, 0x40000
	v_add_u32_e32 v156, 0x14000, v147
	v_lshl_add_u64 v[2:3], s[4:5], 0, v[18:19]
	s_addc_u32 s9, s7, 0
	v_readfirstlane_b32 s11, v156
	global_load_lds_dwordx4 v[2:3], off
	v_lshl_add_u64 v[20:21], s[8:9], 0, v[16:17]
	s_mov_b32 m0, s11
	v_add_u32_e32 v158, 0x16000, v147
	global_load_lds_dwordx4 v[20:21], off
	v_lshl_add_u64 v[20:21], s[8:9], 0, v[18:19]
	v_readfirstlane_b32 s8, v158
	s_mov_b32 m0, s8
	s_add_u32 s8, s4, 0x40000
	v_add_u32_e32 v159, 0x4000, v147
	s_addc_u32 s9, s5, 0
	v_readfirstlane_b32 s11, v159
	global_load_lds_dwordx4 v[20:21], off
	v_lshl_add_u64 v[16:17], s[8:9], 0, v[16:17]
	s_mov_b32 m0, s11
	v_add_u32_e32 v160, 0x6000, v147
	global_load_lds_dwordx4 v[16:17], off
	v_lshl_add_u64 v[16:17], s[8:9], 0, v[18:19]
	v_readfirstlane_b32 s8, v160
	s_mov_b32 m0, s8
	s_nop 0
	global_load_lds_dwordx4 v[16:17], off
	v_ashrrev_i32_e32 v16, 8, v146
	v_cmp_eq_u32_e32 vcc, 1, v16
	s_and_saveexec_b64 s[8:9], vcc
	s_cbranch_execz .LBB0_54
	s_barrier

; __global__ void __launch_bounds__(512, 2) hymba_fwd(Params p) {
;     ...
;   phase_inproj(p, lds);
;   grid.sync();
;   phase_conv(p);
.LBB0_125:
	s_barrier
	s_and_saveexec_b64 s[0:1], s[58:59]
	s_cbranch_execz .LBB0_135
	buffer_wbl2 sc1
	s_waitcnt vmcnt(0)
	s_load_dwordx2 s[4:5], s[92:93], 0x58
	v_mov_b32_e32 v2, 0
	v_readlane_b32 s6, v255, 2
	v_readlane_b32 s7, v255, 61
	v_readlane_b32 vcc_hi, v255, 62
	s_nop 3
	s_add_i32 s7, s7, 1
	v_writelane_b32 v255, s7, 61
	s_lshl_b32 s6, s6, 6
	s_add_i32 s6, s6, 0x1f80800
	v_mov_b32_e32 v1, s6
	s_waitcnt lgkmcnt(0)
	global_load_dword v0, v2, s[4:5] offset:40
	v_mov_b32_e32 v3, 1
	global_atomic_add v3, v1, v3, s[90:91] sc0
	s_waitcnt vmcnt(0)
	v_readfirstlane_b32 s6, v0
	s_nop 3
	s_lshr_b32 vcc_lo, s6, 3
	s_mul_i32 s7, s7, vcc_lo
	v_readfirstlane_b32 s6, v3
	s_nop 3
	s_add_i32 s6, s6, 1
	s_cmp_eq_u32 s6, s7
	s_cbranch_scc0 .Lgb1_poll
	v_mov_b32_e32 v3, vcc_lo
	global_atomic_add v3, v2, v3, s[4:5] offset:32 sc0
	s_waitcnt vmcnt(0)
	v_readfirstlane_b32 s6, v3
	v_readfirstlane_b32 s7, v0
	s_nop 3
	s_and_b32 s6, s6, 0xffff
	s_add_i32 s6, s6, vcc_lo
	s_cmp_eq_u32 s6, s7
	s_cbranch_scc0 .Lgb1_poll
	s_sub_i32 s6, 0x10000, s7
	v_mov_b32_e32 v3, s6
	global_atomic_add v2, v3, s[4:5] offset:32

; __global__ void __launch_bounds__(512, 2) hymba_fwd(Params p) {
;     ...
;   phase_mix(p, lds);
;   grid.sync();
;   phase_ssmnorm(p);
.LBB0_279:
	s_barrier
	s_mov_b64 s[0:1], exec
	v_readlane_b32 s4, v255, 25
	v_readlane_b32 s68, v255, 20
	v_readlane_b32 s18, v255, 39
	v_readlane_b32 s19, v255, 40
	v_readlane_b32 s69, v255, 21
	v_readlane_b32 s6, v255, 27
	v_readlane_b32 s7, v255, 28
	v_readlane_b32 s10, v255, 31
	v_readlane_b32 s11, v255, 32
	v_readlane_b32 s16, v255, 37
	v_readlane_b32 s17, v255, 38
	s_mov_b64 s[62:63], s[18:19]
	v_readlane_b32 s66, v255, 22
	v_readlane_b32 s88, v255, 45
	s_and_b64 s[2:3], s[0:1], s[68:69]
	s_mov_b64 s[60:61], s[16:17]
	s_mov_b64 s[50:51], s[6:7]
	s_mov_b64 s[54:55], s[10:11]
	v_readlane_b32 s64, v255, 24
	v_readlane_b32 s67, v255, 23
	v_readlane_b32 s65, v255, 0
	v_readlane_b32 s70, v255, 1
	v_readlane_b32 s71, v255, 19
	v_readlane_b32 s89, v255, 46
	v_readlane_b32 s5, v255, 26
	v_readlane_b32 s8, v255, 29
	v_readlane_b32 s9, v255, 30
	v_readlane_b32 s12, v255, 33
	v_readlane_b32 s13, v255, 34
	v_readlane_b32 s14, v255, 35
	v_readlane_b32 s15, v255, 36
	s_mov_b64 exec, s[2:3]
	s_cbranch_execz .LBB0_289
	buffer_wbl2 sc1
	s_waitcnt vmcnt(0)
	s_load_dwordx2 s[4:5], s[66:67], 0x58
	v_mov_b32_e32 v2, 0
	v_readlane_b32 s6, v255, 2
	v_readlane_b32 s7, v255, 61
	v_readlane_b32 vcc_hi, v255, 62
	s_nop 3
	s_add_i32 s7, s7, 1
	v_writelane_b32 v255, s7, 61
	s_lshl_b32 s6, s6, 6
	s_add_i32 s6, s6, 0x1f80800
	v_mov_b32_e32 v1, s6
	s_waitcnt lgkmcnt(0)
	global_load_dword v0, v2, s[4:5] offset:40
	v_mov_b32_e32 v3, 1
	global_atomic_add v3, v1, v3, s[90:91] sc0
	s_waitcnt vmcnt(0)
	v_readfirstlane_b32 s6, v0
	s_nop 3
	s_lshr_b32 vcc_lo, s6, 3
	s_mul_i32 s7, s7, vcc_lo
	v_readfirstlane_b32 s6, v3
	s_nop 3
	s_add_i32 s6, s6, 1
	s_cmp_eq_u32 s6, s7
	s_cbranch_scc0 .Lgb3_poll
	v_mov_b32_e32 v3, vcc_lo
	global_atomic_add v3, v2, v3, s[4:5] offset:32 sc0
	s_waitcnt vmcnt(0)
	v_readfirstlane_b32 s6, v3
	v_readfirstlane_b32 s7, v0
	s_nop 3
	s_and_b32 s6, s6, 0xffff
	s_add_i32 s6, s6, vcc_lo
	s_cmp_eq_u32 s6, s7
	s_cbranch_scc0 .Lgb3_poll
	s_sub_i32 s6, 0x10000, s7
	v_mov_b32_e32 v3, s6
	global_atomic_add v2, v3, s[4:5] offset:32

; __global__ void __launch_bounds__(512, 2) hymba_fwd(Params p) {
;     ...
;   phase_ssmnorm(p);
;   grid.sync();
;   phase_outproj(p, lds);
.LBB0_300:
	s_or_b64 exec, exec, s[0:1]
	s_barrier
	s_and_saveexec_b64 s[0:1], s[68:69]
	v_readlane_b32 s51, v255, 2
	s_cbranch_execz .LBB0_310
	buffer_wbl2 sc1
	s_waitcnt vmcnt(0)
	s_load_dwordx2 s[4:5], s[66:67], 0x58
	v_mov_b32_e32 v2, 0
	v_readlane_b32 s6, v255, 2
	v_readlane_b32 s7, v255, 61
	v_readlane_b32 vcc_hi, v255, 62
	s_nop 3
	s_add_i32 s7, s7, 1
	v_writelane_b32 v255, s7, 61
	s_lshl_b32 s6, s6, 6
	s_add_i32 s6, s6, 0x1f80800
	v_mov_b32_e32 v1, s6
	s_waitcnt lgkmcnt(0)
	global_load_dword v0, v2, s[4:5] offset:40
	v_mov_b32_e32 v3, 1
	global_atomic_add v3, v1, v3, s[90:91] sc0
	s_waitcnt vmcnt(0)
	v_readfirstlane_b32 s6, v0
	s_nop 3
	s_lshr_b32 vcc_lo, s6, 3
	s_mul_i32 s7, s7, vcc_lo
	v_readfirstlane_b32 s6, v3
	s_nop 3
	s_add_i32 s6, s6, 1
	s_cmp_eq_u32 s6, s7
	s_cbranch_scc0 .Lgb4_poll
	v_mov_b32_e32 v3, vcc_lo
	global_atomic_add v3, v2, v3, s[4:5] offset:32 sc0
	s_waitcnt vmcnt(0)
	v_readfirstlane_b32 s6, v3
	v_readfirstlane_b32 s7, v0
	s_nop 3
	s_and_b32 s6, s6, 0xffff
	s_add_i32 s6, s6, vcc_lo
	s_cmp_eq_u32 s6, s7
	s_cbranch_scc0 .Lgb4_poll
	s_sub_i32 s6, 0x10000, s7
	v_mov_b32_e32 v3, s6
	global_atomic_add v2, v3, s[4:5] offset:32

; __global__ void __launch_bounds__(512, 2) hymba_fwd(Params p) {
;     ...
;   phase_outproj(p, lds);
;   grid.sync();
;   phase_norm2(p);
.LBB0_323:
	s_barrier
	s_and_saveexec_b64 s[2:3], s[68:69]
	s_cbranch_execz .LBB0_333
	buffer_wbl2 sc1
	s_waitcnt vmcnt(0)
	s_load_dwordx2 s[4:5], s[66:67], 0x58
	v_mov_b32_e32 v2, 0
	v_readlane_b32 s6, v255, 2
	v_readlane_b32 s7, v255, 61
	v_readlane_b32 vcc_hi, v255, 62
	s_nop 3
	s_add_i32 s7, s7, 1
	v_writelane_b32 v255, s7, 61
	s_lshl_b32 s6, s6, 6
	s_add_i32 s6, s6, 0x1f80800
	v_mov_b32_e32 v1, s6
	s_waitcnt lgkmcnt(0)
	global_load_dword v0, v2, s[4:5] offset:40
	v_mov_b32_e32 v3, 1
	global_atomic_add v3, v1, v3, s[90:91] sc0
	s_waitcnt vmcnt(0)
	v_readfirstlane_b32 s6, v0
	s_nop 3
	s_lshr_b32 vcc_lo, s6, 3
	s_mul_i32 s7, s7, vcc_lo
	v_readfirstlane_b32 s6, v3
	s_nop 3
	s_add_i32 s6, s6, 1
	s_cmp_eq_u32 s6, s7
	s_cbranch_scc0 .Lgb5_poll
	v_mov_b32_e32 v3, vcc_lo
	global_atomic_add v3, v2, v3, s[4:5] offset:32 sc0
	s_waitcnt vmcnt(0)
	v_readfirstlane_b32 s6, v3
	v_readfirstlane_b32 s7, v0
	s_nop 3
	s_and_b32 s6, s6, 0xffff
	s_add_i32 s6, s6, vcc_lo
	s_cmp_eq_u32 s6, s7
	s_cbranch_scc0 .Lgb5_poll
	s_sub_i32 s6, 0x10000, s7
	v_mov_b32_e32 v3, s6
	global_atomic_add v2, v3, s[4:5] offset:32

; __global__ void __launch_bounds__(512, 2) hymba_fwd(Params p) {
;     ...
;   phase_norm2(p);
;   grid.sync();
;   phase_up(p, lds);
.LBB0_342:
	s_or_b64 exec, exec, s[10:11]
	s_waitcnt lgkmcnt(0)
	s_barrier
	s_and_saveexec_b64 s[2:3], s[68:69]
	s_cbranch_execz .LBB0_352
	buffer_wbl2 sc1
	s_waitcnt vmcnt(0)
	s_load_dwordx2 s[4:5], s[66:67], 0x58
	v_mov_b32_e32 v2, 0
	v_readlane_b32 s6, v255, 2
	v_readlane_b32 s7, v255, 61
	v_readlane_b32 vcc_hi, v255, 62
	s_nop 3
	s_add_i32 s7, s7, 1
	v_writelane_b32 v255, s7, 61
	s_lshl_b32 s6, s6, 6
	s_add_i32 s6, s6, 0x1f80800
	v_mov_b32_e32 v1, s6
	s_waitcnt lgkmcnt(0)
	global_load_dword v0, v2, s[4:5] offset:40
	v_mov_b32_e32 v3, 1
	global_atomic_add v3, v1, v3, s[90:91] sc0
	s_waitcnt vmcnt(0)
	v_readfirstlane_b32 s6, v0
	s_nop 3
	s_lshr_b32 vcc_lo, s6, 3
	s_mul_i32 s7, s7, vcc_lo
	v_readfirstlane_b32 s6, v3
	s_nop 3
	s_add_i32 s6, s6, 1
	s_cmp_eq_u32 s6, s7
	s_cbranch_scc0 .Lgb6_poll
	v_mov_b32_e32 v3, vcc_lo
	global_atomic_add v3, v2, v3, s[4:5] offset:32 sc0
	s_waitcnt vmcnt(0)
	v_readfirstlane_b32 s6, v3
	v_readfirstlane_b32 s7, v0
	s_nop 3
	s_and_b32 s6, s6, 0xffff
	s_add_i32 s6, s6, vcc_lo
	s_cmp_eq_u32 s6, s7
	s_cbranch_scc0 .Lgb6_poll
	s_sub_i32 s6, 0x10000, s7
	v_mov_b32_e32 v3, s6
	global_atomic_add v2, v3, s[4:5] offset:32

; __global__ void __launch_bounds__(512, 2) hymba_fwd(Params p) {
;     ...
;   phase_down(p, lds);
;   grid.sync();
;   phase_final(p);
.LBB0_388:
	s_barrier
	s_and_saveexec_b64 s[0:1], s[68:69]
	s_cbranch_execz .LBB0_398
	buffer_wbl2 sc1
	s_waitcnt vmcnt(0)
	s_load_dwordx2 s[4:5], s[66:67], 0x58
	v_mov_b32_e32 v2, 0
	v_readlane_b32 s6, v255, 2
	v_readlane_b32 s7, v255, 61
	v_readlane_b32 vcc_hi, v255, 62
	s_nop 3
	s_add_i32 s7, s7, 1
	v_writelane_b32 v255, s7, 61
	s_lshl_b32 s6, s6, 6
	s_add_i32 s6, s6, 0x1f80800
	v_mov_b32_e32 v1, s6
	s_waitcnt lgkmcnt(0)
	global_load_dword v0, v2, s[4:5] offset:40
	v_mov_b32_e32 v3, 1
	global_atomic_add v3, v1, v3, s[90:91] sc0
	s_waitcnt vmcnt(0)
	v_readfirstlane_b32 s6, v0
	s_nop 3
	s_lshr_b32 vcc_lo, s6, 3
	s_mul_i32 s7, s7, vcc_lo
	v_readfirstlane_b32 s6, v3
	s_nop 3
	s_add_i32 s6, s6, 1
	s_cmp_eq_u32 s6, s7
	s_cbranch_scc0 .Lgb8_poll
	v_mov_b32_e32 v3, vcc_lo
	global_atomic_add v3, v2, v3, s[4:5] offset:32 sc0
	s_waitcnt vmcnt(0)
	v_readfirstlane_b32 s6, v3
	v_readfirstlane_b32 s7, v0
	s_nop 3
	s_and_b32 s6, s6, 0xffff
	s_add_i32 s6, s6, vcc_lo
	s_cmp_eq_u32 s6, s7
	s_cbranch_scc0 .Lgb8_poll
	s_sub_i32 s6, 0x10000, s7
	v_mov_b32_e32 v3, s6
	global_atomic_add v2, v3, s[4:5] offset:32
